# diff far tiles: scaled scores formed against the old running max while the row-max chain resolves (ILP), recompute only when the reference moves; on top of previous
# speedup vs baseline: 1.0421x; 1.0035x over previous
.LBB0_258:
	s_andn2_saveexec_b64 s[22:23], s[22:23]
	s_cbranch_execz .LBB0_260
	s_nop 7
	s_nop 7
	s_nop 3
	v_sub_f32_e32 v243, v198, v226
	v_max3_f32 v244, v96, v97, v80
	v_fma_f32 v112, v96, v178, v243
	v_fma_f32 v128, v80, v178, v243
	v_max3_f32 v245, v98, v99, v81
	v_fma_f32 v113, v97, v178, v243
	v_fma_f32 v129, v81, v178, v243
	v_max3_f32 v244, v244, v82, v83
	v_fma_f32 v114, v98, v178, v243
	v_fma_f32 v130, v82, v178, v243
	v_max3_f32 v245, v245, v102, v103
	v_fma_f32 v115, v99, v178, v243
	v_fma_f32 v131, v83, v178, v243
	v_max3_f32 v244, v244, v100, v101
	v_fma_f32 v116, v100, v178, v243
	v_fma_f32 v132, v84, v178, v243
	v_max3_f32 v245, v245, v86, v87
	v_fma_f32 v117, v101, v178, v243
	v_fma_f32 v133, v85, v178, v243
	v_max3_f32 v244, v244, v84, v85
	v_fma_f32 v118, v102, v178, v243
	v_fma_f32 v134, v86, v178, v243
	v_max3_f32 v245, v245, v106, v107
	v_fma_f32 v119, v103, v178, v243
	v_fma_f32 v135, v87, v178, v243
	v_max3_f32 v244, v244, v104, v105
	v_fma_f32 v120, v104, v178, v243
	v_fma_f32 v136, v88, v178, v243
	v_max3_f32 v245, v245, v90, v91
	v_fma_f32 v121, v105, v178, v243
	v_fma_f32 v137, v89, v178, v243
	v_max3_f32 v244, v244, v88, v89
	v_fma_f32 v122, v106, v178, v243
	v_fma_f32 v138, v90, v178, v243
	v_max3_f32 v245, v245, v110, v111
	v_fma_f32 v123, v107, v178, v243
	v_fma_f32 v139, v91, v178, v243
	v_max3_f32 v244, v244, v108, v109
	v_fma_f32 v124, v108, v178, v243
	v_fma_f32 v140, v92, v178, v243
	v_max3_f32 v245, v245, v94, v95
	v_fma_f32 v125, v109, v178, v243
	v_fma_f32 v141, v93, v178, v243
	v_max3_f32 v244, v244, v92, v93
	v_fma_f32 v126, v110, v178, v243
	v_fma_f32 v142, v94, v178, v243
	v_fma_f32 v127, v111, v178, v243
	v_fma_f32 v143, v95, v178, v243
	v_max_f32_e32 v244, v244, v245
	v_mov_b32_e32 v245, v244
	s_nop 1
	v_permlane32_swap_b32_e32 v244, v245
	v_max_f32_e32 v244, v244, v245
	v_fmamk_f32 v244, v244, 0x3e38aa3b, v198
	v_sub_f32_e32 v245, v244, v226
	v_cmp_lt_f32_e32 vcc, s45, v245
	s_cmp_eq_u64 vcc, 0
	v_max_f32_e32 v244, v228, v244
	s_cselect_b64 vcc, -1, 0
	v_cndmask_b32_e32 v227, v244, v226, vcc
	v_cmp_neq_f32_e32 vcc, v227, v226
	s_nop 4
	s_cbranch_vccz .Ldf_far_nofix
	v_sub_f32_e32 v243, v198, v227
	v_fma_f32 v112, v96, v178, v243
	v_fma_f32 v128, v80, v178, v243
	v_fma_f32 v113, v97, v178, v243
	v_fma_f32 v129, v81, v178, v243
	v_fma_f32 v114, v98, v178, v243
	v_fma_f32 v130, v82, v178, v243
	v_fma_f32 v115, v99, v178, v243
	v_fma_f32 v131, v83, v178, v243
	v_fma_f32 v116, v100, v178, v243
	v_fma_f32 v132, v84, v178, v243
	v_fma_f32 v117, v101, v178, v243
	v_fma_f32 v133, v85, v178, v243
	v_fma_f32 v118, v102, v178, v243
	v_fma_f32 v134, v86, v178, v243
	v_fma_f32 v119, v103, v178, v243
	v_fma_f32 v135, v87, v178, v243
	v_fma_f32 v120, v104, v178, v243
	v_fma_f32 v136, v88, v178, v243
	v_fma_f32 v121, v105, v178, v243
	v_fma_f32 v137, v89, v178, v243
	v_fma_f32 v122, v106, v178, v243
	v_fma_f32 v138, v90, v178, v243
	v_fma_f32 v123, v107, v178, v243
	v_fma_f32 v139, v91, v178, v243
	v_fma_f32 v124, v108, v178, v243
	v_fma_f32 v140, v92, v178, v243
	v_fma_f32 v125, v109, v178, v243
	v_fma_f32 v141, v93, v178, v243
	v_fma_f32 v126, v110, v178, v243
	v_fma_f32 v142, v94, v178, v243
	v_fma_f32 v127, v111, v178, v243
	v_fma_f32 v143, v95, v178, v243
.Ldf_far_nofix:
.LBB0_260:
	s_or_b64 exec, exec, s[22:23]
	v_cmp_neq_f32_e32 vcc, v227, v226
	ds_read_b64_tr_b16 v[80:81], v0 offset:20480
	ds_read_b64_tr_b16 v[82:83], v14 offset:22528
	ds_read_b64_tr_b16 v[84:85], v15 offset:20480
	ds_read_b64_tr_b16 v[86:87], v221 offset:22528
	ds_read_b64_tr_b16 v[88:89], v222 offset:20480
	ds_read_b64_tr_b16 v[90:91], v223 offset:22528
	ds_read_b64_tr_b16 v[92:93], v224 offset:20480
	ds_read_b64_tr_b16 v[94:95], v225 offset:22528
	v_exp_f32_e32 v104, v112
	v_exp_f32_e32 v105, v113
	v_exp_f32_e32 v106, v114
	v_exp_f32_e32 v107, v115
	v_exp_f32_e32 v108, v116
	v_exp_f32_e32 v109, v117
	v_exp_f32_e32 v110, v118
	v_exp_f32_e32 v111, v119
	s_cbranch_vccz .Ldf_norescale
	v_sub_f32_e32 v246, v226, v227
	v_exp_f32_e32 v246, v246
	s_nop 0
	v_mul_f32_e32 v219, v219, v246
	v_pk_mul_f32 v[78:79], v[78:79], v[246:247] op_sel_hi:[1,0]
	v_pk_mul_f32 v[76:77], v[76:77], v[246:247] op_sel_hi:[1,0]
	v_pk_mul_f32 v[74:75], v[74:75], v[246:247] op_sel_hi:[1,0]
	v_pk_mul_f32 v[72:73], v[72:73], v[246:247] op_sel_hi:[1,0]
	v_pk_mul_f32 v[70:71], v[70:71], v[246:247] op_sel_hi:[1,0]
	v_pk_mul_f32 v[68:69], v[68:69], v[246:247] op_sel_hi:[1,0]
	v_pk_mul_f32 v[66:67], v[66:67], v[246:247] op_sel_hi:[1,0]
	v_pk_mul_f32 v[64:65], v[64:65], v[246:247] op_sel_hi:[1,0]
	v_pk_mul_f32 v[62:63], v[62:63], v[246:247] op_sel_hi:[1,0]
	v_pk_mul_f32 v[60:61], v[60:61], v[246:247] op_sel_hi:[1,0]
	v_pk_mul_f32 v[58:59], v[58:59], v[246:247] op_sel_hi:[1,0]
	v_pk_mul_f32 v[56:57], v[56:57], v[246:247] op_sel_hi:[1,0]
	v_pk_mul_f32 v[54:55], v[54:55], v[246:247] op_sel_hi:[1,0]
	v_pk_mul_f32 v[52:53], v[52:53], v[246:247] op_sel_hi:[1,0]
	v_pk_mul_f32 v[50:51], v[50:51], v[246:247] op_sel_hi:[1,0]
	v_pk_mul_f32 v[48:49], v[48:49], v[246:247] op_sel_hi:[1,0]
	v_pk_mul_f32 v[46:47], v[46:47], v[246:247] op_sel_hi:[1,0]
	v_pk_mul_f32 v[44:45], v[44:45], v[246:247] op_sel_hi:[1,0]
	v_pk_mul_f32 v[42:43], v[42:43], v[246:247] op_sel_hi:[1,0]
	v_pk_mul_f32 v[40:41], v[40:41], v[246:247] op_sel_hi:[1,0]
	v_pk_mul_f32 v[38:39], v[38:39], v[246:247] op_sel_hi:[1,0]
	v_pk_mul_f32 v[36:37], v[36:37], v[246:247] op_sel_hi:[1,0]
	v_pk_mul_f32 v[34:35], v[34:35], v[246:247] op_sel_hi:[1,0]
	v_pk_mul_f32 v[32:33], v[32:33], v[246:247] op_sel_hi:[1,0]
	v_pk_mul_f32 v[30:31], v[30:31], v[246:247] op_sel_hi:[1,0]
	v_pk_mul_f32 v[28:29], v[28:29], v[246:247] op_sel_hi:[1,0]
	v_pk_mul_f32 v[26:27], v[26:27], v[246:247] op_sel_hi:[1,0]
	v_pk_mul_f32 v[24:25], v[24:25], v[246:247] op_sel_hi:[1,0]
	v_pk_mul_f32 v[22:23], v[22:23], v[246:247] op_sel_hi:[1,0]
	v_pk_mul_f32 v[20:21], v[20:21], v[246:247] op_sel_hi:[1,0]
	v_pk_mul_f32 v[18:19], v[18:19], v[246:247] op_sel_hi:[1,0]
	v_pk_mul_f32 v[16:17], v[16:17], v[246:247] op_sel_hi:[1,0]
